# DSA loop VALU/MFMA interleave + score loop double-accumulator pipeline
# speedup vs baseline: 1.0284x; 1.0088x over previous
; #define MFMA(a, b, c) __builtin_amdgcn_mfma_f32_32x32x16_bf16((a), (b), (c), 0, 0, 0)
; template <int MODE>
; DI void attn_item(const u16* Qp, int ldq, const u16* Kp, int ldk, const u16* VTp, int ldv, u16* Op, int ldo,
;                   int q0, int nkt, const float* Fc, const unsigned* BM, float kmaxn, char* smem) {
;     ...
;     for (int g4 = 0; g4 < 4; ++g4) {
;       const int k2 = g4 >> 1, s2 = g4 & 1;
;       const f32x16 zero16 = {0.f, 0.f, 0.f, 0.f, 0.f, 0.f, 0.f, 0.f, 0.f, 0.f, 0.f, 0.f, 0.f, 0.f, 0.f, 0.f};
; #pragma unroll
;       for (int st = s2 * 4; st < s2 * 4 + 4; ++st) {
;         bf16x8 a = *(const bf16x8*)(sKn + kro + k2 * 8192 + (((st * 2 + h) ^ ksw) << 4));
;         sn[k2] = (st == 0) ? MFMA(a, qf[st], zero16) : MFMA(a, qf[st], sn[k2]);
;       }
;       const unsigned wbits = k2 ? bw.y : bw.x;
;       float pv8[8];
; #pragma unroll
;       for (int e8 = 0; e8 < 8; ++e8) {
;         const int e = 8 * s2 + e8;
;         float pv;
;         if (MODE == 1) {
;           const float x = sc[k2][e];
;           pv = __builtin_amdgcn_exp2f(x - m_run);
;           if (diag) pv = (x <= -1e29f) ? 0.f : pv;
;         } else {
;           pv = __builtin_amdgcn_exp2f(sc[k2][e] * c1 - m_run);
;           if (MODE == 2) {
;             const int kb = 16 * ((e >> 2) >> 1) + 8 * h + 4 * ((e >> 2) & 1) + (e & 3);
;             const int msk = __builtin_amdgcn_sbfe(wbits, kb, 1);
;             pv = __int_as_float(__float_as_int(pv) & msk);
;           }
;         }
;         pv8[e8] = pv; ps += pv;
;       }
;       u32x4 u;
;       u[0] = pk2(pv8[0], pv8[1]); u[1] = pk2(pv8[2], pv8[3]); u[2] = pk2(pv8[4], pv8[5]); u[3] = pk2(pv8[6], pv8[7]);
;       const bf16x8 pfg = __builtin_bit_cast(bf16x8, u);
; #pragma unroll
;       for (int dt = 0; dt < 4; ++dt) {
;         bf16x8 a = *(const bf16x8*)(sV + vro + dt * 4096 + (((4 * k2 + 2 * s2 + h) ^ vsw) << 4));
;         o[dt] = MFMA(a, pfg, o[dt]);
;       }
;       __builtin_amdgcn_sched_barrier(0);
;     }
.LBB0_494:
	s_add_i32 s15, s14, 0xffff0000
	s_and_b32 s15, s15, 0x18000
	v_add_u32_e32 v252, s15, v172
	s_add_i32 s15, s14, 0xfffe8000
	s_and_b32 s15, s15, 0x18000
	v_add_u32_e32 v211, s15, v204
	v_add_u32_e32 v203, v252, v173
	v_add_u32_e32 v205, v252, v174
	v_add_u32_e32 v207, v252, v175
	v_add_u32_e32 v209, v252, v176
	v_add_u32_e32 v217, v211, v190
	ds_read_b128 v[224:227], v203
	ds_read_b128 v[228:231], v205
	ds_read_b128 v[232:235], v207
	ds_read_b128 v[236:239], v209
	ds_read_b128 v[240:243], v217 offset:16384
	ds_read_b128 v[244:247], v217 offset:20480
	ds_read_b128 v[248:251], v217 offset:24576
	ds_read_b128 v[212:215], v217 offset:28672
	v_fma_f32 v0, v96, s33, -v206
	v_fma_f32 v14, v97, s33, -v206
	v_fma_f32 v96, v98, s33, -v206
	v_fma_f32 v98, v99, s33, -v206
	s_waitcnt lgkmcnt(7)
	v_mfma_f32_32x32x16_bf16 v[112:127], v[224:227], v[128:131], 0
	v_add_u32_e32 v216, v252, v177
	ds_read_b128 v[224:227], v216
	v_fma_f32 v100, v100, s33, -v206
	v_exp_f32_e32 v14, v14
	v_exp_f32_e32 v98, v98
	v_fma_f32 v101, v101, s33, -v206
	v_exp_f32_e32 v96, v96
	s_waitcnt lgkmcnt(7)
	v_mfma_f32_32x32x16_bf16 v[112:127], v[228:231], v[132:135], v[112:127]
	v_add_u32_e32 v216, v252, v178
	ds_read_b128 v[228:231], v216
	v_bfe_i32 v15, v168, v183, 1
	v_bfe_i32 v99, v168, v185, 1
	v_exp_f32_e32 v208, v0
	v_and_b32_e32 v14, v15, v14
	s_waitcnt lgkmcnt(7)
	v_mfma_f32_32x32x16_bf16 v[112:127], v[232:235], v[136:139], v[112:127]
	v_add_u32_e32 v216, v252, v179
	ds_read_b128 v[232:235], v216
	v_exp_f32_e32 v4, v100
	v_exp_f32_e32 v5, v101
	v_bfe_i32 v6, v168, v186, 1
	v_and_b32_e32 v15, v99, v98
	v_and_b32_e32 v98, v6, v4
	v_fma_f32 v4, v102, s33, -v206
	v_bfe_i32 v97, v168, v184, 1
	s_waitcnt lgkmcnt(7)
	v_mfma_f32_32x32x16_bf16 v[112:127], v[236:239], v[140:143], v[112:127]
	v_add_u32_e32 v216, v252, v180
	ds_read_b128 v[236:239], v216
	v_bfe_i32 v7, v168, v187, 1
	v_exp_f32_e32 v8, v4
	v_fma_f32 v4, v103, s33, -v206
	v_and_b32_e32 v96, v97, v96
	v_and_b32_e32 v97, v7, v5
	v_exp_f32_e32 v9, v4
	v_bfe_i32 v13, v168, v170, 1
	v_bfe_i32 v10, v168, v188, 1
	v_bfe_i32 v11, v168, v189, 1
	v_and_b32_e32 v13, v13, v208
	v_and_b32_e32 v100, v11, v9
	v_and_b32_e32 v101, v10, v8
	v_cvt_pk_bf16_f32 v8, v13, v14
	v_cvt_pk_bf16_f32 v9, v96, v15
	v_cvt_pk_bf16_f32 v10, v98, v97
	v_cvt_pk_bf16_f32 v11, v101, v100
	v_add_u32_e32 v217, v211, v199
	s_waitcnt lgkmcnt(7)
	s_nop 0
	v_mfma_f32_32x32x16_bf16 v[64:79], v[240:243], v[8:11], v[64:79]
	ds_read_b128 v[240:243], v217 offset:16384
	v_add_f32_e32 v4, 0, v13
	v_add_f32_e32 v4, v4, v14
	s_waitcnt lgkmcnt(7)
	v_mfma_f32_32x32x16_bf16 v[48:63], v[244:247], v[8:11], v[48:63]
	ds_read_b128 v[244:247], v217 offset:20480
	v_add_f32_e32 v4, v4, v96
	v_add_f32_e32 v4, v4, v15
	s_waitcnt lgkmcnt(7)
	v_mfma_f32_32x32x16_bf16 v[32:47], v[248:251], v[8:11], v[32:47]
	ds_read_b128 v[248:251], v217 offset:24576
	v_add_f32_e32 v4, v4, v98
	v_add_f32_e32 v4, v4, v97
	s_waitcnt lgkmcnt(7)
	v_mfma_f32_32x32x16_bf16 v[16:31], v[212:215], v[8:11], v[16:31]
	ds_read_b128 v[212:215], v217 offset:28672
	v_add_f32_e32 v4, v4, v101
	v_add_f32_e32 v96, v4, v100
	s_waitcnt lgkmcnt(7)
	v_mfma_f32_32x32x16_bf16 v[112:127], v[224:227], v[144:147], v[112:127]
	ds_read_b128 v[224:227], v203 offset:8192
	v_fma_f32 v8, v104, s33, -v206
	v_fma_f32 v10, v105, s33, -v206
	v_exp_f32_e32 v8, v8
	v_exp_f32_e32 v10, v10
	v_bfe_i32 v9, v168, v191, 1
	v_bfe_i32 v11, v168, v192, 1
	v_and_b32_e32 v98, v9, v8
	v_and_b32_e32 v97, v11, v10
	s_waitcnt lgkmcnt(7)
	v_mfma_f32_32x32x16_bf16 v[112:127], v[228:231], v[148:151], v[112:127]
	ds_read_b128 v[228:231], v205 offset:8192
	v_fma_f32 v8, v106, s33, -v206
	v_fma_f32 v10, v107, s33, -v206
	v_exp_f32_e32 v8, v8
	v_exp_f32_e32 v10, v10
	v_bfe_i32 v9, v168, v193, 1
	v_bfe_i32 v11, v168, v194, 1
	v_and_b32_e32 v100, v9, v8
	v_and_b32_e32 v99, v11, v10
	s_waitcnt lgkmcnt(7)
	v_mfma_f32_32x32x16_bf16 v[112:127], v[232:235], v[152:155], v[112:127]
	ds_read_b128 v[232:235], v207 offset:8192
	v_fma_f32 v8, v108, s33, -v206
	v_fma_f32 v10, v109, s33, -v206
	v_exp_f32_e32 v8, v8
	v_exp_f32_e32 v10, v10
	v_bfe_i32 v9, v168, v195, 1
	v_bfe_i32 v11, v168, v196, 1
	v_and_b32_e32 v101, v11, v10
	v_and_b32_e32 v102, v9, v8
	s_waitcnt lgkmcnt(7)
	v_mfma_f32_32x32x16_bf16 v[112:127], v[236:239], v[156:159], v[112:127]
	ds_read_b128 v[236:239], v209 offset:8192
	v_fma_f32 v8, v110, s33, -v206
	v_fma_f32 v10, v111, s33, -v206
	v_exp_f32_e32 v8, v8
	v_exp_f32_e32 v10, v10
	v_bfe_i32 v9, v168, v197, 1
	v_bfe_i32 v11, v168, v198, 1
	v_and_b32_e32 v104, v9, v8
	v_and_b32_e32 v103, v11, v10
	v_cvt_pk_bf16_f32 v8, v98, v97
	v_cvt_pk_bf16_f32 v9, v100, v99
	v_cvt_pk_bf16_f32 v10, v102, v101
	v_cvt_pk_bf16_f32 v11, v104, v103
	v_add_u32_e32 v217, v211, v200
	s_waitcnt lgkmcnt(7)
	s_nop 0
	v_mfma_f32_32x32x16_bf16 v[64:79], v[240:243], v[8:11], v[64:79]
	ds_read_b128 v[240:243], v217 offset:16384
	v_add_f32_e32 v253, v96, v98
	v_add_f32_e32 v253, v253, v97
	s_waitcnt lgkmcnt(7)
	v_mfma_f32_32x32x16_bf16 v[48:63], v[244:247], v[8:11], v[48:63]
	ds_read_b128 v[244:247], v217 offset:20480
	v_add_f32_e32 v253, v253, v100
	v_add_f32_e32 v253, v253, v99
	s_waitcnt lgkmcnt(7)
	v_mfma_f32_32x32x16_bf16 v[32:47], v[248:251], v[8:11], v[32:47]
	ds_read_b128 v[248:251], v217 offset:24576
	v_add_f32_e32 v253, v253, v102
	v_add_f32_e32 v253, v253, v101
	s_waitcnt lgkmcnt(7)
; template <int MODE>
; DI void attn_item(const u16* Qp, int ldq, const u16* Kp, int ldk, const u16* VTp, int ldv, u16* Op, int ldo,
;                   int q0, int nkt, const float* Fc, const unsigned* BM, float kmaxn, char* smem) {
;     ...
;     for (int g4 = 0; g4 < 4; ++g4) {
;       const int k2 = g4 >> 1, s2 = g4 & 1;
;       const f32x16 zero16 = {0.f, 0.f, 0.f, 0.f, 0.f, 0.f, 0.f, 0.f, 0.f, 0.f, 0.f, 0.f, 0.f, 0.f, 0.f, 0.f};
; #pragma unroll
;       for (int st = s2 * 4; st < s2 * 4 + 4; ++st) {
;         bf16x8 a = *(const bf16x8*)(sKn + kro + k2 * 8192 + (((st * 2 + h) ^ ksw) << 4));
;         sn[k2] = (st == 0) ? MFMA(a, qf[st], zero16) : MFMA(a, qf[st], sn[k2]);
;       }
;       const unsigned wbits = k2 ? bw.y : bw.x;
;       float pv8[8];
; #pragma unroll
;       for (int e8 = 0; e8 < 8; ++e8) {
;         const int e = 8 * s2 + e8;
;         float pv;
;         if (MODE == 1) {
;           const float x = sc[k2][e];
;           pv = __builtin_amdgcn_exp2f(x - m_run);
;           if (diag) pv = (x <= -1e29f) ? 0.f : pv;
;         } else {
;           pv = __builtin_amdgcn_exp2f(sc[k2][e] * c1 - m_run);
;           if (MODE == 2) {
;             const int kb = 16 * ((e >> 2) >> 1) + 8 * h + 4 * ((e >> 2) & 1) + (e & 3);
;             const int msk = __builtin_amdgcn_sbfe(wbits, kb, 1);
;             pv = __int_as_float(__float_as_int(pv) & msk);
;           }
;         }
;         pv8[e8] = pv; ps += pv;
;       }
;       u32x4 u;
;       u[0] = pk2(pv8[0], pv8[1]); u[1] = pk2(pv8[2], pv8[3]); u[2] = pk2(pv8[4], pv8[5]); u[3] = pk2(pv8[6], pv8[7]);
;       const bf16x8 pfg = __builtin_bit_cast(bf16x8, u);
; #pragma unroll
;       for (int dt = 0; dt < 4; ++dt) {
;         bf16x8 a = *(const bf16x8*)(sV + vro + dt * 4096 + (((4 * k2 + 2 * s2 + h) ^ vsw) << 4));
;         o[dt] = MFMA(a, pfg, o[dt]);
;       }
;       __builtin_amdgcn_sched_barrier(0);
;     }
;     l_run += ps;
;     asm volatile("s_waitcnt vmcnt(4)" ::: "memory");
;     if (MODE == 1 && tid < 16) *(f32x4*)(fct + ((kt + 1) & 3) * 64 + tid * 4) = rf;
;     if (MODE == 1) {
;       const int v = __all((qkb - flast) < (m_run - 160.f)) ? 1 : 0;
;       if (lane == 0) votes[(kt & 1) * 8 + wave] = v;
;     }
;     asm volatile("s_waitcnt lgkmcnt(0)" ::: "memory");
;     __builtin_amdgcn_s_barrier();
;     asm volatile("" ::: "memory");
;     sc[0] = sn[0]; sc[1] = sn[1]; bw = bwn;
	v_mfma_f32_32x32x16_bf16 v[16:31], v[212:215], v[8:11], v[16:31]
	ds_read_b128 v[212:215], v217 offset:28672
	v_add_f32_e32 v253, v253, v104
	v_add_f32_e32 v168, v253, v103
	s_waitcnt lgkmcnt(7)
	v_mfma_f32_32x32x16_bf16 v[96:111], v[224:227], v[128:131], 0
	v_add_u32_e32 v216, v252, v177
	ds_read_b128 v[224:227], v216 offset:8192
	v_fma_f32 v8, v80, s33, -v206
	v_fma_f32 v10, v81, s33, -v206
	v_exp_f32_e32 v8, v8
	v_exp_f32_e32 v10, v10
	v_bfe_i32 v9, v169, v170, 1
	v_bfe_i32 v11, v169, v183, 1
	v_and_b32_e32 v81, v9, v8
	v_and_b32_e32 v80, v11, v10
	s_waitcnt lgkmcnt(7)
	v_mfma_f32_32x32x16_bf16 v[96:111], v[228:231], v[132:135], v[96:111]
	v_add_u32_e32 v216, v252, v178
	ds_read_b128 v[228:231], v216 offset:8192
	v_fma_f32 v8, v82, s33, -v206
	v_fma_f32 v10, v83, s33, -v206
	v_exp_f32_e32 v8, v8
	v_exp_f32_e32 v10, v10
	v_bfe_i32 v9, v169, v184, 1
	v_bfe_i32 v11, v169, v185, 1
	v_and_b32_e32 v83, v9, v8
	v_and_b32_e32 v82, v11, v10
	s_waitcnt lgkmcnt(7)
	v_mfma_f32_32x32x16_bf16 v[96:111], v[232:235], v[136:139], v[96:111]
	v_add_u32_e32 v216, v252, v179
	ds_read_b128 v[232:235], v216 offset:8192
	v_fma_f32 v8, v84, s33, -v206
	v_fma_f32 v10, v85, s33, -v206
	v_exp_f32_e32 v8, v8
	v_exp_f32_e32 v10, v10
	v_bfe_i32 v9, v169, v186, 1
	v_bfe_i32 v11, v169, v187, 1
	v_and_b32_e32 v85, v9, v8
	v_and_b32_e32 v84, v11, v10
	s_waitcnt lgkmcnt(7)
	v_mfma_f32_32x32x16_bf16 v[96:111], v[236:239], v[140:143], v[96:111]
	v_add_u32_e32 v216, v252, v180
	ds_read_b128 v[236:239], v216 offset:8192
	v_fma_f32 v8, v86, s33, -v206
	v_fma_f32 v10, v87, s33, -v206
	v_exp_f32_e32 v8, v8
	v_exp_f32_e32 v10, v10
	v_bfe_i32 v9, v169, v188, 1
	v_bfe_i32 v11, v169, v189, 1
	v_and_b32_e32 v87, v9, v8
	v_and_b32_e32 v86, v11, v10
	v_cvt_pk_bf16_f32 v8, v81, v80
	v_cvt_pk_bf16_f32 v9, v83, v82
	v_cvt_pk_bf16_f32 v10, v85, v84
	v_cvt_pk_bf16_f32 v11, v87, v86
	v_add_u32_e32 v217, v211, v202
	s_waitcnt lgkmcnt(7)
	s_nop 0
	v_mfma_f32_32x32x16_bf16 v[64:79], v[240:243], v[8:11], v[64:79]
	ds_read_b128 v[240:243], v217 offset:16384
	v_add_f32_e32 v253, v168, v81
	v_add_f32_e32 v253, v253, v80
	s_waitcnt lgkmcnt(7)
	v_mfma_f32_32x32x16_bf16 v[48:63], v[244:247], v[8:11], v[48:63]
	ds_read_b128 v[244:247], v217 offset:20480
	v_add_f32_e32 v253, v253, v83
	v_add_f32_e32 v253, v253, v82
	s_waitcnt lgkmcnt(7)
	v_mfma_f32_32x32x16_bf16 v[32:47], v[248:251], v[8:11], v[32:47]
	ds_read_b128 v[248:251], v217 offset:24576
	v_add_f32_e32 v253, v253, v85
	v_add_f32_e32 v253, v253, v84
	s_waitcnt lgkmcnt(7)
	v_mfma_f32_32x32x16_bf16 v[16:31], v[212:215], v[8:11], v[16:31]
	ds_read_b128 v[212:215], v217 offset:28672
	v_add_f32_e32 v253, v253, v87
	v_add_f32_e32 v12, v253, v86
	s_waitcnt lgkmcnt(7)
	v_mfma_f32_32x32x16_bf16 v[96:111], v[224:227], v[144:147], v[96:111]
	v_fma_f32 v4, v88, s33, -v206
	v_fma_f32 v6, v89, s33, -v206
	v_exp_f32_e32 v4, v4
	v_exp_f32_e32 v6, v6
	v_bfe_i32 v5, v169, v191, 1
	v_bfe_i32 v7, v169, v192, 1
	v_and_b32_e32 v14, v5, v4
	v_and_b32_e32 v13, v7, v6
	s_waitcnt lgkmcnt(6)
	v_mfma_f32_32x32x16_bf16 v[96:111], v[228:231], v[148:151], v[96:111]
	v_fma_f32 v4, v90, s33, -v206
	v_fma_f32 v6, v91, s33, -v206
	v_exp_f32_e32 v4, v4
	v_exp_f32_e32 v6, v6
	v_bfe_i32 v5, v169, v193, 1
	v_bfe_i32 v7, v169, v194, 1
	v_and_b32_e32 v80, v5, v4
	v_and_b32_e32 v15, v7, v6
	s_waitcnt lgkmcnt(5)
	v_mfma_f32_32x32x16_bf16 v[96:111], v[232:235], v[152:155], v[96:111]
	v_fma_f32 v4, v92, s33, -v206
	v_fma_f32 v6, v93, s33, -v206
	v_exp_f32_e32 v4, v4
	v_exp_f32_e32 v6, v6
	v_bfe_i32 v5, v169, v195, 1
	v_bfe_i32 v7, v169, v196, 1
	v_and_b32_e32 v82, v5, v4
	v_and_b32_e32 v81, v7, v6
	s_waitcnt lgkmcnt(4)
	v_mfma_f32_32x32x16_bf16 v[96:111], v[236:239], v[156:159], v[96:111]
	v_fma_f32 v4, v94, s33, -v206
	v_fma_f32 v6, v95, s33, -v206
	v_exp_f32_e32 v4, v4
	v_exp_f32_e32 v6, v6
	v_bfe_i32 v5, v169, v197, 1
	v_bfe_i32 v7, v169, v198, 1
	v_and_b32_e32 v84, v5, v4
	v_and_b32_e32 v83, v7, v6
	v_cvt_pk_bf16_f32 v4, v14, v13
	v_cvt_pk_bf16_f32 v5, v80, v15
	v_cvt_pk_bf16_f32 v6, v82, v81
	v_cvt_pk_bf16_f32 v7, v84, v83
	s_waitcnt lgkmcnt(3)
	s_nop 0
	v_mfma_f32_32x32x16_bf16 v[64:79], v[240:243], v[4:7], v[64:79]
	s_waitcnt lgkmcnt(2)
	v_mfma_f32_32x32x16_bf16 v[48:63], v[244:247], v[4:7], v[48:63]
	s_waitcnt lgkmcnt(1)
	v_mfma_f32_32x32x16_bf16 v[32:47], v[248:251], v[4:7], v[32:47]
	v_add_f32_e32 v0, v12, v14
	v_add_f32_e32 v0, v0, v13
	v_add_f32_e32 v0, v0, v80
	v_add_f32_e32 v0, v0, v15
	v_add_f32_e32 v0, v0, v82
	v_add_f32_e32 v0, v0, v81
	s_waitcnt lgkmcnt(0)
	v_mfma_f32_32x32x16_bf16 v[16:31], v[212:215], v[4:7], v[16:31]
	v_add_f32_e32 v0, v0, v84
	v_add_f32_e32 v0, v0, v83
	s_waitcnt vmcnt(4)
	s_waitcnt lgkmcnt(0)
	s_barrier
	s_add_i32 s14, s14, 0x8000
	v_add_f32_e32 v182, v182, v0
	s_cmp_lg_u32 s12, s13
	s_cbranch_scc0 .LBB0_489
	v_mov_b64_e32 v[80:81], v[96:97]
	v_mov_b64_e32 v[82:83], v[98:99]
	v_mov_b64_e32 v[84:85], v[100:101]
	v_mov_b64_e32 v[86:87], v[102:103]
	v_mov_b64_e32 v[88:89], v[104:105]
	v_mov_b64_e32 v[90:91], v[106:107]
	v_mov_b64_e32 v[92:93], v[108:109]
	v_mov_b64_e32 v[94:95], v[110:111]
	v_mov_b64_e32 v[96:97], v[112:113]
	v_mov_b64_e32 v[98:99], v[114:115]
	v_mov_b64_e32 v[100:101], v[116:117]
	v_mov_b64_e32 v[102:103], v[118:119]
	v_mov_b64_e32 v[104:105], v[120:121]
	v_mov_b64_e32 v[106:107], v[122:123]
	v_mov_b64_e32 v[108:109], v[124:125]
	v_mov_b64_e32 v[110:111], v[126:127]
	s_waitcnt vmcnt(0)
	v_mov_b64_e32 v[168:169], v[2:3]
	s_branch .LBB0_492

; #define MFMA(a, b, c) __builtin_amdgcn_mfma_f32_32x32x16_bf16((a), (b), (c), 0, 0, 0)
; #define BID opqs((int)blockIdx.x)
; DI void score_phase(const Params& p, char* smem) {
;     ...
;   for (int idx = BID; idx < 512; idx += gridDim.x) {
;     const int half = idx & 1, b = (idx >> 1) & 1, t = idx >> 2;
;     const int blk = (t < 64) ? (127 - t) : (t - 64);
;     const int n = (blk + 1) * 64, ntile = n >> 5;
;     const int nt_lo = half ? (ntile >> 1) : 0, nt_hi = half ? ntile : (ntile >> 1);
;     const int t0 = blk * 64 + wave * 8;
;     const u16* Hb = H + (size_t)b * S_ * HLD;
;     bf16x8 af[4][4];
; #pragma unroll
;     for (int rt = 0; rt < 4; ++rt) {
;       const int tokA = t0 + 2 * rt + ((r >> 2) & 1), head = (r >> 3) * 4 + (r & 3);
; #pragma unroll
;       for (int st = 0; st < 4; ++st) af[rt][st] = *(const bf16x8*)(Hb + (size_t)tokA * HLD + 3072 + head * 64 + st * 16 + 8 * h);
;     }
;     wl[lane] = AUX[(size_t)(b * S_ + t0) * 16 + lane] * 0.125f;
;     wl[64 + lane] = AUX[(size_t)(b * S_ + t0) * 16 + 64 + lane] * 0.125f;
;     __syncthreads();
;     float* scb = SC + (size_t)b * SCB + (size_t)2048 * blk * (blk + 1);
;     bf16x8 bfr[4], bnx[4];
; #pragma unroll
;     for (int st = 0; st < 4; ++st) bfr[st] = *(const bf16x8*)(Hb + (size_t)(nt_lo * 32 + r) * HLD + 4096 + st * 16 + 8 * h);
; #pragma unroll 1
;     for (int nt2 = nt_lo; nt2 < nt_hi; ++nt2) {
;       const int k0 = nt2 * 32;
;       const int kn = (nt2 + 1 < nt_hi) ? (k0 + 32) : k0;
; #pragma unroll
;       for (int st = 0; st < 4; ++st) bnx[st] = *(const bf16x8*)(Hb + (size_t)(kn + r) * HLD + 4096 + st * 16 + 8 * h);
; #pragma unroll
;       for (int rt = 0; rt < 4; ++rt) {
;         f32x16 acc;
; #pragma unroll
;         for (int e = 0; e < 16; ++e) acc[e] = 0.f;
; #pragma unroll
;         for (int st = 0; st < 4; ++st) acc = MFMA(af[rt][st], bfr[st], acc);
.LBB0_820:
	s_ashr_i32 s7, s10, 2
	s_and_b32 s16, s10, 1
	s_bfe_i32 s6, s10, 0x10000
	s_bfe_u32 s8, s10, 0x10001
	s_sub_i32 s9, 0x7f, s7
	s_sub_i32 s15, s7, 64
	s_cmp_lt_i32 s7, 64
	s_cselect_b32 s18, s9, s15
	s_add_i32 s9, s18, 1
	s_and_b32 s15, s6, s9
	s_lshl_b32 s17, s18, 6
	s_mul_i32 s6, s8, 0x5400000
	s_add_u32 s6, s11, s6
	v_add_u32_e32 v2, s17, v198
	s_addc_u32 s7, s12, 0
	v_or_b32_e32 v3, v2, v199
	v_mov_b64_e32 v[4:5], s[6:7]
	s_movk_i32 s22, 0x2a00
	v_mad_i64_i32 v[6:7], s[20:21], v3, s22, v[4:5]
	v_mov_b32_e32 v183, v1
	v_lshl_add_u64 v[6:7], v[6:7], 0, v[182:183]
	v_lshl_add_u64 v[6:7], v[6:7], 0, v[0:1]
	s_mov_b64 s[24:25], 0x1800
	s_movk_i32 s19, 0x1000
	v_lshl_add_u64 v[8:9], v[6:7], 0, s[24:25]
	v_add_co_u32_e32 v6, vcc, s19, v6
	s_lshl_b32 s16, s9, s16
	s_nop 0
	v_addc_co_u32_e32 v7, vcc, 0, v7, vcc
	global_load_dwordx4 v[18:21], v[8:9], off offset:32
	global_load_dwordx4 v[22:25], v[8:9], off offset:64
	global_load_dwordx4 v[26:29], v[6:7], off offset:2048
	global_load_dwordx4 v[30:33], v[8:9], off offset:96
	v_or_b32_e32 v6, 2, v3
	v_mad_i64_i32 v[6:7], s[20:21], v6, s22, v[4:5]
	v_lshl_add_u64 v[6:7], v[6:7], 0, v[182:183]
	v_lshl_add_u64 v[6:7], v[6:7], 0, v[0:1]
	v_lshl_add_u64 v[8:9], v[6:7], 0, s[24:25]
	v_add_co_u32_e32 v6, vcc, s19, v6
	s_cmp_ge_i32 s15, s16
	s_nop 0
	v_addc_co_u32_e32 v7, vcc, 0, v7, vcc
	global_load_dwordx4 v[34:37], v[8:9], off offset:32
	global_load_dwordx4 v[38:41], v[8:9], off offset:64
	global_load_dwordx4 v[42:45], v[6:7], off offset:2048
	global_load_dwordx4 v[46:49], v[8:9], off offset:96
	v_or_b32_e32 v6, 4, v3
	v_mad_i64_i32 v[6:7], s[20:21], v6, s22, v[4:5]
	v_lshl_add_u64 v[6:7], v[6:7], 0, v[182:183]
	v_lshl_add_u64 v[6:7], v[6:7], 0, v[0:1]
	v_lshl_add_u64 v[8:9], v[6:7], 0, s[24:25]
	v_add_co_u32_e32 v6, vcc, s19, v6
	v_or_b32_e32 v3, 6, v3
	s_nop 0
	v_addc_co_u32_e32 v7, vcc, 0, v7, vcc
	global_load_dwordx4 v[50:53], v[8:9], off offset:32
	global_load_dwordx4 v[54:57], v[8:9], off offset:64
	global_load_dwordx4 v[58:61], v[6:7], off offset:2048
	global_load_dwordx4 v[62:65], v[8:9], off offset:96
	v_mad_i64_i32 v[4:5], s[20:21], v3, s22, v[4:5]
	v_lshl_add_u32 v8, s8, 13, v2
	v_lshl_add_u64 v[4:5], v[4:5], 0, v[182:183]
	v_ashrrev_i32_e32 v9, 31, v8
	v_lshl_add_u64 v[4:5], v[4:5], 0, v[0:1]
	v_lshlrev_b64 v[8:9], 6, v[8:9]
	v_lshl_add_u64 v[6:7], v[4:5], 0, s[24:25]
	v_lshl_add_u64 v[8:9], v[180:181], 0, v[8:9]
	v_add_co_u32_e32 v4, vcc, s19, v4
	global_load_dword v3, v[8:9], off
	s_nop 0
	global_load_dword v8, v[8:9], off offset:256
	v_addc_co_u32_e32 v5, vcc, 0, v5, vcc
	global_load_dwordx4 v[66:69], v[6:7], off offset:32
	global_load_dwordx4 v[70:73], v[6:7], off offset:64
	global_load_dwordx4 v[74:77], v[4:5], off offset:2048
	global_load_dwordx4 v[78:81], v[6:7], off offset:96
	s_movk_i32 s23, 0x2000
	s_mov_b64 s[24:25], 0x2000
	s_waitcnt vmcnt(0)
	v_mul_f32_e32 v3, 0x3e000000, v3
	v_mul_f32_e32 v4, 0x3e000000, v8
	ds_write2st64_b32 v200, v3, v4 offset1:1
	s_waitcnt lgkmcnt(0)
	s_barrier
	s_cbranch_scc1 .LBB0_819
	s_mul_i32 s8, s8, 0x8100000
	s_add_u32 s8, s13, s8
	s_mul_hi_i32 s19, s18, s9
	s_mul_i32 s18, s18, s9
	s_addc_u32 s20, s14, 0
	s_lshl_b64 s[18:19], s[18:19], 13
	s_add_u32 s18, s8, s18
	s_addc_u32 s19, s20, s19
	s_lshl_b32 s8, s15, 5
	v_or_b32_e32 v3, s8, v178
	v_mov_b64_e32 v[4:5], s[6:7]
	v_mad_i64_i32 v[4:5], s[20:21], v3, s22, v[4:5]
	v_lshl_add_u64 v[4:5], v[4:5], 0, v[0:1]
	v_lshl_add_u64 v[6:7], v[4:5], 0, s[24:25]
	v_add_co_u32_e32 v4, vcc, s23, v4
	global_load_dwordx4 v[162:165], v[6:7], off offset:96
	s_nop 0
	v_addc_co_u32_e32 v5, vcc, 0, v5, vcc
	global_load_dwordx4 v[174:177], v[4:5], off
	global_load_dwordx4 v[170:173], v[6:7], off offset:32
	global_load_dwordx4 v[166:169], v[6:7], off offset:64
	ds_read_b128 v[82:85], v202
	ds_read_b128 v[86:89], v202 offset:16
	ds_read_b128 v[90:93], v202 offset:32
	ds_read_b128 v[94:97], v202 offset:48
	ds_read_b128 v[98:101], v202 offset:128
	ds_read_b128 v[102:105], v202 offset:144
	ds_read_b128 v[106:109], v202 offset:160
	ds_read_b128 v[110:113], v202 offset:176
	ds_read_b128 v[114:117], v202 offset:256
	ds_read_b128 v[118:121], v202 offset:272
	ds_read_b128 v[122:125], v202 offset:288
	ds_read_b128 v[126:129], v202 offset:304
	ds_read_b128 v[130:133], v202 offset:384
	ds_read_b128 v[134:137], v202 offset:400
	ds_read_b128 v[138:141], v202 offset:416
	ds_read_b128 v[142:145], v202 offset:432
	v_or_b32_e32 v2, v2, v179
	v_subrev_u32_e32 v2, s17, v2
	s_lshl_b32 s9, s9, 6
	v_mov_b32_e32 v185, v1
	v_or_b32_e32 v3, 2, v2
	v_lshl_add_u64 v[186:187], s[18:19], 0, v[184:185]
	v_mad_i64_i32 v[188:189], s[18:19], v2, s9, 0
	v_mad_i64_i32 v[190:191], s[18:19], v3, s9, 0
	v_or_b32_e32 v3, 4, v2
	v_or_b32_e32 v2, 6, v2
	v_mad_i64_i32 v[192:193], s[18:19], v3, s9, 0
	v_mad_i64_i32 v[194:195], s[18:19], v2, s9, 0
	s_waitcnt vmcnt(0) lgkmcnt(0)
	v_mfma_f32_32x32x16_bf16 v[2:17], v[26:29], v[174:177], 0
	v_mfma_f32_32x32x16_bf16 v[2:17], v[18:21], v[170:173], v[2:17]
	v_mfma_f32_32x32x16_bf16 v[2:17], v[22:25], v[166:169], v[2:17]
	v_mfma_f32_32x32x16_bf16 v[2:17], v[30:33], v[162:165], v[2:17]
; #define MFMA(a, b, c) __builtin_amdgcn_mfma_f32_32x32x16_bf16((a), (b), (c), 0, 0, 0)
; DI void score_phase(const Params& p, char* smem) {
;     ...
;     for (int nt2 = nt_lo; nt2 < nt_hi; ++nt2) {
;       const int k0 = nt2 * 32;
;       const int kn = (nt2 + 1 < nt_hi) ? (k0 + 32) : k0;
; #pragma unroll
;       for (int st = 0; st < 4; ++st) bnx[st] = *(const bf16x8*)(Hb + (size_t)(kn + r) * HLD + 4096 + st * 16 + 8 * h);
; #pragma unroll
;       for (int rt = 0; rt < 4; ++rt) {
;         f32x16 acc;
; #pragma unroll
;         for (int e = 0; e < 16; ++e) acc[e] = 0.f;
; #pragma unroll
;         for (int st = 0; st < 4; ++st) acc = MFMA(af[rt][st], bfr[st], acc);
;         float s = 0.f;
; #pragma unroll
;         for (int e4 = 0; e4 < 4; ++e4) {
;           const f32x4 wv = *(const f32x4*)(wl + (2 * rt + h) * 16 + e4 * 4);
; #pragma unroll
;           for (int i = 0; i < 4; ++i) s += fmaxf(acc[e4 * 4 + i], 0.f) * wv[i];
;         }
;         const int row = (t0 + 2 * rt + h) - blk * 64;
;         __builtin_nontemporal_store(s, scb + (size_t)row * n + k0 + r);
;       }
; #pragma unroll
;       for (int st = 0; st < 4; ++st) bfr[st] = bnx[st];
;     }
.LBB0_822:
	s_add_i32 s15, s15, 1
	s_add_i32 s17, s8, 32
	s_cmp_lt_i32 s15, s16
	s_cselect_b32 s18, s17, s8
	v_or_b32_e32 v244, s18, v178
	v_mov_b64_e32 v[246:247], s[6:7]
	v_mad_i64_i32 v[246:247], s[18:19], v244, s22, v[246:247]
	v_lshl_add_u64 v[246:247], v[246:247], 0, v[0:1]
	v_lshl_add_u64 v[248:249], v[246:247], 0, s[24:25]
	v_add_co_u32_e32 v246, vcc, s23, v246
	s_ashr_i32 s9, s8, 31
	s_nop 0
	v_addc_co_u32_e32 v247, vcc, 0, v247, vcc
	global_load_dwordx4 v[154:157], v[246:247], off
	global_load_dwordx4 v[150:153], v[248:249], off offset:32
	global_load_dwordx4 v[146:149], v[248:249], off offset:64
	global_load_dwordx4 v[158:161], v[248:249], off offset:96
	v_lshl_add_u64 v[196:197], s[8:9], 2, v[186:187]
	s_cmp_ge_i32 s15, s16
	s_mov_b32 s8, s17
	v_mfma_f32_32x32x16_bf16 v[224:239], v[42:45], v[174:177], 0
	v_max_f32_e32 v240, 0, v2
	v_fma_f32 v183, v82, v240, 0
	v_max_f32_e32 v241, 0, v3
	v_fmac_f32_e32 v183, v83, v241
	v_max_f32_e32 v240, 0, v4
	v_fmac_f32_e32 v183, v84, v240
	v_max_f32_e32 v241, 0, v5
	v_fmac_f32_e32 v183, v85, v241
	v_mfma_f32_32x32x16_bf16 v[224:239], v[34:37], v[170:173], v[224:239]
	v_max_f32_e32 v240, 0, v6
	v_fmac_f32_e32 v183, v86, v240
	v_max_f32_e32 v241, 0, v7
	v_fmac_f32_e32 v183, v87, v241
	v_max_f32_e32 v240, 0, v8
	v_fmac_f32_e32 v183, v88, v240
	v_max_f32_e32 v241, 0, v9
	v_fmac_f32_e32 v183, v89, v241
	v_mfma_f32_32x32x16_bf16 v[224:239], v[38:41], v[166:169], v[224:239]
	v_max_f32_e32 v240, 0, v10
	v_fmac_f32_e32 v183, v90, v240
	v_max_f32_e32 v241, 0, v11
	v_fmac_f32_e32 v183, v91, v241
	v_max_f32_e32 v240, 0, v12
	v_fmac_f32_e32 v183, v92, v240
	v_max_f32_e32 v241, 0, v13
	v_fmac_f32_e32 v183, v93, v241
	v_mfma_f32_32x32x16_bf16 v[224:239], v[46:49], v[162:165], v[224:239]
	v_max_f32_e32 v240, 0, v14
	v_fmac_f32_e32 v183, v94, v240
	v_max_f32_e32 v241, 0, v15
	v_fmac_f32_e32 v183, v95, v241
	v_max_f32_e32 v240, 0, v16
	v_fmac_f32_e32 v183, v96, v240
	v_max_f32_e32 v241, 0, v17
	v_fmac_f32_e32 v183, v97, v241
	v_lshl_add_u64 v[242:243], v[188:189], 2, v[196:197]
	global_store_dword v[242:243], v183, off nt
	s_nop 1
	v_mfma_f32_32x32x16_bf16 v[2:17], v[58:61], v[174:177], 0
	v_max_f32_e32 v240, 0, v224
	v_fma_f32 v183, v98, v240, 0
	v_max_f32_e32 v241, 0, v225
	v_fmac_f32_e32 v183, v99, v241
	v_max_f32_e32 v240, 0, v226
	v_fmac_f32_e32 v183, v100, v240
	v_max_f32_e32 v241, 0, v227
	v_fmac_f32_e32 v183, v101, v241
	v_mfma_f32_32x32x16_bf16 v[2:17], v[50:53], v[170:173], v[2:17]
	v_max_f32_e32 v240, 0, v228
	v_fmac_f32_e32 v183, v102, v240
	v_max_f32_e32 v241, 0, v229
	v_fmac_f32_e32 v183, v103, v241
	v_max_f32_e32 v240, 0, v230
	v_fmac_f32_e32 v183, v104, v240
	v_max_f32_e32 v241, 0, v231
	v_fmac_f32_e32 v183, v105, v241
	v_mfma_f32_32x32x16_bf16 v[2:17], v[54:57], v[166:169], v[2:17]
	v_max_f32_e32 v240, 0, v232
	v_fmac_f32_e32 v183, v106, v240
	v_max_f32_e32 v241, 0, v233
	v_fmac_f32_e32 v183, v107, v241
	v_max_f32_e32 v240, 0, v234
	v_fmac_f32_e32 v183, v108, v240
	v_max_f32_e32 v241, 0, v235
	v_fmac_f32_e32 v183, v109, v241
	v_mfma_f32_32x32x16_bf16 v[2:17], v[62:65], v[162:165], v[2:17]
	v_max_f32_e32 v240, 0, v236
	v_fmac_f32_e32 v183, v110, v240
	v_max_f32_e32 v241, 0, v237
	v_fmac_f32_e32 v183, v111, v241
	v_max_f32_e32 v240, 0, v238
	v_fmac_f32_e32 v183, v112, v240
	v_max_f32_e32 v241, 0, v239
	v_fmac_f32_e32 v183, v113, v241
	v_lshl_add_u64 v[242:243], v[190:191], 2, v[196:197]
	global_store_dword v[242:243], v183, off nt
	s_nop 1
	v_mfma_f32_32x32x16_bf16 v[224:239], v[74:77], v[174:177], 0
	v_max_f32_e32 v240, 0, v2
	v_fma_f32 v183, v114, v240, 0
	v_max_f32_e32 v241, 0, v3
	v_fmac_f32_e32 v183, v115, v241
	v_max_f32_e32 v240, 0, v4
	v_fmac_f32_e32 v183, v116, v240
	v_max_f32_e32 v241, 0, v5
	v_fmac_f32_e32 v183, v117, v241
	v_mfma_f32_32x32x16_bf16 v[224:239], v[66:69], v[170:173], v[224:239]
	v_max_f32_e32 v240, 0, v6
	v_fmac_f32_e32 v183, v118, v240
	v_max_f32_e32 v241, 0, v7
	v_fmac_f32_e32 v183, v119, v241
	v_max_f32_e32 v240, 0, v8
	v_fmac_f32_e32 v183, v120, v240
	v_max_f32_e32 v241, 0, v9
	v_fmac_f32_e32 v183, v121, v241
	v_mfma_f32_32x32x16_bf16 v[224:239], v[70:73], v[166:169], v[224:239]
	v_max_f32_e32 v240, 0, v10
	v_fmac_f32_e32 v183, v122, v240
	v_max_f32_e32 v241, 0, v11
	v_fmac_f32_e32 v183, v123, v241
	v_max_f32_e32 v240, 0, v12
	v_fmac_f32_e32 v183, v124, v240
	v_max_f32_e32 v241, 0, v13
	v_fmac_f32_e32 v183, v125, v241
	v_mfma_f32_32x32x16_bf16 v[224:239], v[78:81], v[162:165], v[224:239]
	v_max_f32_e32 v240, 0, v14
	v_fmac_f32_e32 v183, v126, v240
	v_max_f32_e32 v241, 0, v15
	v_fmac_f32_e32 v183, v127, v241
	v_max_f32_e32 v240, 0, v16
	v_fmac_f32_e32 v183, v128, v240
	v_max_f32_e32 v241, 0, v17
	v_fmac_f32_e32 v183, v129, v241
	v_lshl_add_u64 v[242:243], v[192:193], 2, v[196:197]
	global_store_dword v[242:243], v183, off nt
	s_nop 1
	s_waitcnt vmcnt(3)
	v_mov_b64_e32 v[174:175], v[154:155]
	v_mov_b64_e32 v[176:177], v[156:157]
	v_mov_b64_e32 v[170:171], v[150:151]
	v_mov_b64_e32 v[172:173], v[152:153]
	v_mov_b64_e32 v[166:167], v[146:147]
	v_mov_b64_e32 v[168:169], v[148:149]
	v_mov_b64_e32 v[162:163], v[158:159]
	v_mov_b64_e32 v[164:165], v[160:161]
	v_mfma_f32_32x32x16_bf16 v[2:17], v[26:29], v[174:177], 0
	v_max_f32_e32 v240, 0, v224
	v_fma_f32 v183, v130, v240, 0
	v_max_f32_e32 v241, 0, v225
	v_fmac_f32_e32 v183, v131, v241
	v_max_f32_e32 v240, 0, v226
	v_fmac_f32_e32 v183, v132, v240
	v_max_f32_e32 v241, 0, v227
	v_fmac_f32_e32 v183, v133, v241
	v_mfma_f32_32x32x16_bf16 v[2:17], v[18:21], v[170:173], v[2:17]
	v_max_f32_e32 v240, 0, v228
	v_fmac_f32_e32 v183, v134, v240
	v_max_f32_e32 v241, 0, v229
	v_fmac_f32_e32 v183, v135, v241
	v_max_f32_e32 v240, 0, v230
	v_fmac_f32_e32 v183, v136, v240
	v_max_f32_e32 v241, 0, v231
	v_fmac_f32_e32 v183, v137, v241
	v_mfma_f32_32x32x16_bf16 v[2:17], v[22:25], v[166:169], v[2:17]
	v_max_f32_e32 v240, 0, v232
	v_fmac_f32_e32 v183, v138, v240
	v_max_f32_e32 v241, 0, v233
	v_fmac_f32_e32 v183, v139, v241
	v_max_f32_e32 v240, 0, v234
	v_fmac_f32_e32 v183, v140, v240
	v_max_f32_e32 v241, 0, v235
	v_fmac_f32_e32 v183, v141, v241
	v_mfma_f32_32x32x16_bf16 v[2:17], v[30:33], v[162:165], v[2:17]
	v_max_f32_e32 v240, 0, v236
	v_fmac_f32_e32 v183, v142, v240
	v_max_f32_e32 v241, 0, v237
	v_fmac_f32_e32 v183, v143, v241
	v_max_f32_e32 v240, 0, v238
	v_fmac_f32_e32 v183, v144, v240
	v_max_f32_e32 v241, 0, v239
	v_fmac_f32_e32 v183, v145, v241
	v_lshl_add_u64 v[242:243], v[194:195], 2, v[196:197]
	global_store_dword v[242:243], v183, off nt
	s_nop 1
	s_cbranch_scc0 .LBB0_822
	s_branch .LBB0_819
